# GA loop: one static s_setprio 1 for waves 4-7 before the loop, all per-segment priority flips in the loop deleted
# speedup vs baseline: 1.0000x; 1.0000x over previous
.LBB0_1273:
	s_andn2_b64 vcc, exec, s[0:1]
	s_cbranch_vccnz .LBB0_1287
	s_lshl_b32 s0, s22, 1
	s_addk_i32 s0, 0xfeb0
	v_mov_b32_e32 v20, v201
	v_add_u32_e32 v8, s0, v149
	v_lshlrev_b32_e32 v0, 6, v8
	v_lshrrev_b32_e32 v6, 1, v20
	v_and_b32_e32 v2, 32, v6
	s_movk_i32 s0, 0xfc0
	v_ashrrev_i32_e32 v106, 7, v8
	v_bfe_u32 v5, v8, 6, 1
	v_and_or_b32 v0, v0, s0, v2
	v_mov_b64_e32 v[2:3], s[42:43]
	s_mov_b32 s0, 0x220000
	v_mad_i64_i32 v[2:3], s[0:1], v106, s0, v[2:3]
	v_lshlrev_b32_e32 v4, 7, v5
	v_and_or_b32 v110, v6, 64, v4
	v_mov_b64_e32 v[6:7], s[58:59]
	s_mov_b32 s0, 0x110000
	v_add_u32_e32 v108, 0x100, v0
	v_lshlrev_b32_e32 v0, 1, v110
	v_mad_i64_i32 v[6:7], s[0:1], v106, s0, v[6:7]
	v_and_b32_e32 v107, 15, v20
	v_bfe_u32 v21, v20, 4, 2
	v_lshl_add_u64 v[2:3], v[2:3], 0, v[0:1]
	v_lshlrev_b32_e32 v0, 6, v5
	v_mov_b32_e32 v5, v1
	s_movk_i32 s0, 0xff80
	v_lshl_add_u64 v[4:5], v[6:7], 0, v[4:5]
	v_and_or_b32 v6, v8, s0, v0
	v_or_b32_e32 v7, v108, v107
	v_lshlrev_b32_e32 v0, 4, v21
	v_lshl_add_u64 v[2:3], v[2:3], 0, v[0:1]
	v_lshlrev_b32_e32 v0, 9, v7
	v_lshl_add_u64 v[2:3], v[2:3], 0, v[0:1]
	s_movk_i32 s0, 0x2000
	global_load_dwordx4 v[46:49], v[2:3], off
	global_load_dwordx4 v[42:45], v[2:3], off offset:64
	v_add_co_u32_e32 v2, vcc, s0, v2
	v_and_b32_e32 v22, 7, v20
	s_nop 0
	v_addc_co_u32_e32 v3, vcc, 0, v3, vcc
	global_load_dwordx4 v[50:53], v[2:3], off
	global_load_dwordx4 v[54:57], v[2:3], off offset:64
	v_mov_b64_e32 v[2:3], s[44:45]
	v_bfe_u32 v126, v20, 3, 5
	v_lshlrev_b32_e32 v114, 4, v22
	v_mov_b32_e32 v115, v1
	v_mad_i64_i32 v[2:3], s[0:1], v6, s85, v[2:3]
	v_lshl_add_u64 v[116:117], v[4:5], 0, v[114:115]
	v_lshlrev_b32_e32 v0, 8, v126
	v_or_b32_e32 v23, 32, v126
	v_lshl_add_u64 v[18:19], v[2:3], 0, v[114:115]
	v_lshl_add_u64 v[2:3], v[116:117], 0, v[0:1]
	v_lshlrev_b32_e32 v0, 8, v23
	v_mad_u64_u32 v[6:7], s[0:1], v126, s85, v[18:19]
	v_lshl_add_u64 v[10:11], v[116:117], 0, v[0:1]
	v_mad_u64_u32 v[14:15], s[0:1], v23, s85, v[18:19]
	v_mov_b32 v122, 0xc2800000
	global_load_dwordx4 v[2:5], v[2:3], off
	s_nop 0
	global_load_dwordx4 v[6:9], v[6:7], off
	s_nop 0
	global_load_dwordx4 v[10:13], v[10:11], off
	s_nop 0
	global_load_dwordx4 v[14:17], v[14:15], off
	v_lshrrev_b32_e32 v26, 3, v20
	v_lshrrev_b32_e32 v25, 4, v20
	v_xor_b32_e32 v20, v26, v20
	v_lshlrev_b32_e32 v20, 4, v20
	v_and_b32_e32 v132, 0x70, v20
	v_lshlrev_b32_e32 v112, 3, v21
	v_lshlrev_b32_e32 v127, 7, v126
	v_bitop3_b32 v21, v21, v22, 4 bitop3:0x36
	v_add_u32_e32 v20, v150, v132
	v_and_b32_e32 v24, 64, v208
	v_mul_u32_u24_e32 v128, 0x90, v126
	v_lshlrev_b32_e32 v131, 7, v23
	v_lshlrev_b32_e32 v129, 4, v21
	v_add_u32_e32 v21, v20, v127
	v_xor_b32_e32 v0, 16, v208
	v_bitop3_b32 v25, v25, v22, 3 bitop3:0x6c
	v_add3_u32 v22, v150, v114, v128
	v_add_u32_e32 v20, v20, v131
	v_lshlrev_b32_e32 v130, 4, v25
	v_mov_b32_e32 v38, 0
	s_mov_b32 s0, 0
	v_lshlrev_b32_e32 v115, 7, v107
	v_mov_b32_e32 v123, v122
	v_mov_b32_e32 v165, 0
	v_mov_b32_e32 v152, 0x42800000
	v_mov_b32_e32 v153, v152
	v_mov_b32_e32 v154, v152
	v_mov_b32_e32 v155, v152
	v_mov_b32_e32 v156, v152
	v_mov_b32_e32 v157, v152
	v_mov_b32_e32 v158, v152
	v_mov_b32_e32 v159, v152
	v_mul_u32_u24_e32 v109, 0x90, v107
	v_mov_b32_e32 v39, v38
	v_mov_b32_e32 v40, v38
	v_mov_b32_e32 v41, v38
	v_mov_b32_e32 v34, v38
	v_mov_b32_e32 v35, v38
	v_mov_b32_e32 v36, v38
	v_mov_b32_e32 v37, v38
	s_waitcnt vmcnt(0) lgkmcnt(0)
	ds_write_b128 v21, v[2:5]
	ds_write_b128 v22, v[6:9] offset:8192
	ds_write_b128 v20, v[10:13]
	ds_write_b128 v22, v[14:17] offset:12800
	v_add_u32_e32 v2, 64, v24
	v_cmp_lt_i32_e32 vcc, v0, v2
	v_mov_b32_e32 v3, v1
	s_waitcnt lgkmcnt(0)
	v_cndmask_b32_e32 v0, v208, v0, vcc
	v_lshlrev_b32_e32 v111, 2, v0
	v_xor_b32_e32 v0, 32, v208
	v_cmp_lt_i32_e32 vcc, v0, v2
	v_mov_b32_e32 v2, v1
	s_barrier
	v_cndmask_b32_e32 v0, v208, v0, vcc
	v_lshlrev_b32_e32 v113, 2, v0
	v_mul_u32_u24_e32 v0, 0x1100, v126
	v_lshlrev_b32_e32 v0, 1, v0
	v_lshl_add_u64 v[120:121], v[18:19], 0, v[0:1]
	v_mov_b32_e32 v0, v1
	v_mov_b64_e32 v[20:21], v[2:3]
	v_mov_b64_e32 v[24:25], v[2:3]
	v_mov_b64_e32 v[28:29], v[2:3]
	v_mov_b64_e32 v[32:33], v[2:3]
	v_mov_b64_e32 v[12:13], v[2:3]
	v_mov_b64_e32 v[16:17], v[2:3]
	v_mov_b64_e32 v[8:9], v[2:3]
	v_mov_b64_e32 v[18:19], v[0:1]
	v_mov_b64_e32 v[22:23], v[0:1]
	v_mov_b64_e32 v[26:27], v[0:1]
	v_mov_b64_e32 v[30:31], v[0:1]
	v_mov_b64_e32 v[10:11], v[0:1]
	v_mov_b64_e32 v[14:15], v[0:1]
	v_mov_b64_e32 v[6:7], v[0:1]
	v_mov_b64_e32 v[4:5], v[2:3]
	v_mov_b64_e32 v[2:3], v[0:1]
	v_add_u32_e32 v170, v150, v115
	v_add_u32_e32 v171, v170, v129
	v_add_u32_e32 v170, v170, v130
	v_add3_u32 v172, v150, v109, v112
	v_add_u32_e32 v173, 0x2800, v172
	v_add_u32_e32 v174, 0x6400, v172
	v_add_u32_e32 v175, 0x6c00, v172
	v_add_u32_e32 v176, 0x3000, v172
	v_add_u32_e32 v177, 0x3800, v172
	v_add_u32_e32 v178, 0x7400, v172
	v_add_u32_e32 v179, 0x7c00, v172
	v_add_u32_e32 v172, 0x2000, v172
	v_add_u32_e32 v180, v150, v132
	v_add_u32_e32 v181, v180, v131
	v_add_u32_e32 v180, v180, v127
	v_add3_u32 v182, v150, v114, v128
	v_lshlrev_b32_e32 v164, 8, v126
	v_lshl_add_u64 v[184:185], v[116:117], 0, v[164:165]
	s_mov_b64 s[2:3], 0x2000
	v_lshl_add_u64 v[186:187], v[184:185], 0, s[2:3]
	s_mov_b64 s[2:3], 0x44000
	v_lshl_add_u64 v[188:189], v[120:121], 0, s[2:3]
	v_readfirstlane_b32 s1, v149
	s_nop 3
	s_cmp_eq_u32 s1, 1
	s_cbranch_scc0 .Lga_prio_done
	s_setprio 1
.Lga_prio_done:
	s_mov_b32 s1, 1
	v_lshl_or_b32 v68, s1, 6, v126
	v_lshlrev_b32_e32 v0, 8, v68
	s_lshl_b32 s56, s1, 7
	v_lshl_add_u64 v[58:59], v[116:117], 0, v[0:1]
	v_lshl_add_u64 v[66:67], v[120:121], 0, s[56:57]
	v_or_b32_e32 v0, 32, v68
	s_mov_b32 s1, 0x44000
	v_lshlrev_b64 v[68:69], 8, v[0:1]
	v_add_co_u32_e32 v70, vcc, s1, v66
	v_lshl_add_u64 v[68:69], v[116:117], 0, v[68:69]
	s_nop 0
	v_addc_co_u32_e32 v71, vcc, 0, v67, vcc
	global_load_dwordx4 v[58:61], v[58:59], off
	s_nop 0
	global_load_dwordx4 v[62:65], v[66:67], off
	s_nop 0
	global_load_dwordx4 v[66:69], v[68:69], off
	s_nop 0
	global_load_dwordx4 v[70:73], v[70:71], off
.LBB0_1275:
	s_add_i32 s0, s0, 1
	s_add_i32 s1, s0, 1
	s_min_u32 s1, s1, 0x43
	ds_read_b128 v[74:77], v170
	ds_read_b128 v[82:85], v170 offset:2048
	ds_read_b128 v[86:89], v171
	ds_read_b128 v[98:101], v171 offset:2048
	s_lshl_b32 s2, s1, 14
	s_lshl_b32 s56, s1, 7
	v_lshl_add_u64 v[228:229], v[184:185], 0, s[2:3]
	v_lshl_add_u64 v[236:237], v[120:121], 0, s[56:57]
	v_lshl_add_u64 v[238:239], v[186:187], 0, s[2:3]
	v_lshl_add_u64 v[240:241], v[188:189], 0, s[56:57]
	global_load_dwordx4 v[228:231], v[228:229], off
	s_nop 0
	global_load_dwordx4 v[232:235], v[236:237], off
	s_nop 0
	global_load_dwordx4 v[236:239], v[238:239], off
	s_nop 0
	global_load_dwordx4 v[240:243], v[240:241], off
	s_waitcnt lgkmcnt(0)
	v_mfma_f32_16x16x32_bf16 v[78:81], v[74:77], v[46:49], v[152:155]
	v_mfma_f32_16x16x32_bf16 v[74:77], v[74:77], v[50:53], v[156:159]
	v_mfma_f32_16x16x32_bf16 v[94:97], v[86:89], v[42:45], v[78:81]
	v_mfma_f32_16x16x32_bf16 v[78:81], v[86:89], v[54:57], v[74:77]
	v_mfma_f32_16x16x32_bf16 v[74:77], v[82:85], v[46:49], v[152:155]
	v_mfma_f32_16x16x32_bf16 v[90:93], v[98:101], v[42:45], v[74:77]
	v_mfma_f32_16x16x32_bf16 v[74:77], v[82:85], v[50:53], v[156:159]
	ds_read_b128 v[82:85], v170 offset:4096
	ds_read_b128 v[134:137], v170 offset:6144
	v_mfma_f32_16x16x32_bf16 v[74:77], v[98:101], v[54:57], v[74:77]
	ds_read_b128 v[98:101], v171 offset:4096
	ds_read_b128 v[138:141], v171 offset:6144
	s_waitcnt lgkmcnt(0)
	ds_read2_b64 v[212:215], v172 offset1:4
	ds_read2_b64 v[216:219], v172 offset0:8 offset1:12
	ds_read2_b64 v[244:247], v173 offset0:32 offset1:36
	ds_read2_b64 v[248:251], v173 offset0:40 offset1:44
	v_mfma_f32_16x16x32_bf16 v[86:89], v[82:85], v[46:49], v[152:155]
	v_mfma_f32_16x16x32_bf16 v[82:85], v[82:85], v[50:53], v[156:159]
	v_mfma_f32_16x16x32_bf16 v[102:105], v[98:101], v[42:45], v[86:89]
	v_mfma_f32_16x16x32_bf16 v[86:89], v[98:101], v[54:57], v[82:85]
	v_mfma_f32_16x16x32_bf16 v[82:85], v[134:137], v[46:49], v[152:155]
	v_mfma_f32_16x16x32_bf16 v[98:101], v[138:141], v[42:45], v[82:85]
	v_mfma_f32_16x16x32_bf16 v[82:85], v[134:137], v[50:53], v[156:159]
	v_mfma_f32_16x16x32_bf16 v[82:85], v[138:141], v[54:57], v[82:85]
	v_max3_f32 v118, v94, v95, v96
	v_max3_f32 v119, v97, v90, v91
	v_max3_f32 v118, v118, v92, v93
	v_max3_f32 v118, v118, v119, v102
	v_max3_f32 v119, v103, v104, v105
	v_max3_f32 v118, v118, v119, v98
	v_max3_f32 v119, v99, v100, v101
	v_max_f32_e32 v118, v118, v119
	v_mov_b32_e32 v119, v118
	s_nop 1
	v_permlane16_swap_b32_e32 v119, v118
	v_max_f32_e32 v118, v118, v119
	v_mov_b32_e32 v119, v118
	s_nop 1
	v_permlane32_swap_b32_e32 v119, v118
	v_max_f32_e32 v118, v118, v119
	v_cmp_lt_f32_e32 vcc, 0x41000000, v118
	s_cbranch_vccz .LBB0_1277
	v_max_f32_e32 v119, 0, v118
	v_add_f32_e32 v124, v122, v119
	v_exp_f32_e64 v118, -v119
	v_mov_b32_e32 v125, v123
	v_mov_b32_e32 v122, v124
	v_xor_b32_e32 v152, 0x80000000, v124
	v_mov_b32_e32 v153, v152
	v_mov_b32_e32 v154, v152
	v_mov_b32_e32 v155, v152
	v_sub_f32_e32 v94, v94, v119
	v_sub_f32_e32 v95, v95, v119
	v_sub_f32_e32 v96, v96, v119
	v_sub_f32_e32 v97, v97, v119
	v_sub_f32_e32 v90, v90, v119
	v_sub_f32_e32 v91, v91, v119
	v_sub_f32_e32 v92, v92, v119
	v_sub_f32_e32 v93, v93, v119
	v_sub_f32_e32 v102, v102, v119
	v_sub_f32_e32 v103, v103, v119
	v_sub_f32_e32 v104, v104, v119
	v_sub_f32_e32 v105, v105, v119
	v_sub_f32_e32 v98, v98, v119
	v_sub_f32_e32 v99, v99, v119
	v_sub_f32_e32 v100, v100, v119
	v_sub_f32_e32 v101, v101, v119
	v_pk_mul_f32 v[38:39], v[38:39], v[118:119] op_sel_hi:[1,0]
	v_pk_mul_f32 v[40:41], v[40:41], v[118:119] op_sel_hi:[1,0]
	v_pk_mul_f32 v[32:33], v[32:33], v[118:119] op_sel_hi:[1,0]
	v_pk_mul_f32 v[30:31], v[30:31], v[118:119] op_sel_hi:[1,0]
	v_pk_mul_f32 v[24:25], v[24:25], v[118:119] op_sel_hi:[1,0]
	v_pk_mul_f32 v[22:23], v[22:23], v[118:119] op_sel_hi:[1,0]
	v_pk_mul_f32 v[12:13], v[12:13], v[118:119] op_sel_hi:[1,0]
	v_pk_mul_f32 v[10:11], v[10:11], v[118:119] op_sel_hi:[1,0]
	v_pk_mul_f32 v[8:9], v[8:9], v[118:119] op_sel_hi:[1,0]
	v_pk_mul_f32 v[6:7], v[6:7], v[118:119] op_sel_hi:[1,0]
	s_branch .LBB0_1278

.LBB0_1280:
	v_exp_f32_e32 v134, v74
	v_exp_f32_e32 v135, v75
	v_exp_f32_e32 v136, v76
	v_exp_f32_e32 v137, v77
	v_exp_f32_e32 v138, v86
	v_exp_f32_e32 v139, v87
	v_exp_f32_e32 v140, v88
	v_exp_f32_e32 v141, v89
	v_exp_f32_e32 v122, v78
	v_exp_f32_e32 v142, v82
	v_exp_f32_e32 v123, v79
	v_exp_f32_e32 v143, v83
	s_mov_b32 s38, s36
	s_mov_b32 s39, s36
	v_mov_b64_e32 v[118:119], v[124:125]
	v_exp_f32_e32 v124, v80
	v_exp_f32_e32 v144, v84
	v_exp_f32_e32 v125, v85
	s_mov_b32 s37, s36
	v_mov_b64_e32 v[84:85], s[38:39]
	v_exp_f32_e32 v94, v94
	v_exp_f32_e32 v95, v95
	v_exp_f32_e32 v96, v96
	v_exp_f32_e32 v97, v97
	v_exp_f32_e32 v90, v90
	v_exp_f32_e32 v91, v91
	v_exp_f32_e32 v92, v92
	v_exp_f32_e32 v93, v93
	v_exp_f32_e32 v133, v81
	v_mov_b64_e32 v[82:83], s[36:37]
	v_exp_f32_e32 v102, v102
	v_exp_f32_e32 v103, v103
	v_exp_f32_e32 v104, v104
	v_exp_f32_e32 v105, v105
	v_exp_f32_e32 v98, v98
	v_exp_f32_e32 v99, v99
	v_exp_f32_e32 v100, v100
	v_exp_f32_e32 v101, v101
	v_cvt_pk_bf16_f32 v74, v94, v95
	v_cvt_pk_bf16_f32 v75, v96, v97
	v_cvt_pk_bf16_f32 v76, v90, v91
	v_cvt_pk_bf16_f32 v77, v92, v93
	v_cvt_pk_bf16_f32 v86, v122, v123
	v_cvt_pk_bf16_f32 v87, v124, v133
	v_cvt_pk_bf16_f32 v88, v134, v135
	v_cvt_pk_bf16_f32 v89, v136, v137
	v_mfma_f32_16x16x32_bf16 v[38:41], v[82:85], v[74:77], v[38:41]
	v_cvt_pk_bf16_f32 v78, v102, v103
	v_cvt_pk_bf16_f32 v79, v104, v105
	v_cvt_pk_bf16_f32 v80, v98, v99
	v_mfma_f32_16x16x32_bf16 v[34:37], v[82:85], v[86:89], v[34:37]
	v_cvt_pk_bf16_f32 v81, v100, v101
	v_cvt_pk_bf16_f32 v90, v138, v139
	v_cvt_pk_bf16_f32 v91, v140, v141
	v_cvt_pk_bf16_f32 v92, v142, v143
	v_cvt_pk_bf16_f32 v93, v144, v125
	v_mfma_f32_16x16x32_bf16 v[38:41], v[82:85], v[78:81], v[38:41]
	s_nop 0
	v_mfma_f32_16x16x32_bf16 v[34:37], v[82:85], v[90:93], v[34:37]
	s_waitcnt vmcnt(4)
	ds_write_b128 v180, v[58:61] offset:17408
	ds_write_b128 v182, v[62:65] offset:25600
	ds_write_b128 v181, v[66:69] offset:17408
	ds_write_b128 v182, v[70:73] offset:30208
	ds_read2_b64 v[94:97], v176 offset0:64 offset1:68
	ds_read2_b64 v[98:101], v176 offset0:72 offset1:76
	ds_read2_b64 v[102:105], v177 offset0:96 offset1:100
	ds_read2_b64 v[134:137], v177 offset0:104 offset1:108
	s_waitcnt lgkmcnt(4)
	v_mfma_f32_16x16x32_bf16 v[30:33], v[212:215], v[74:77], v[30:33]
	v_mfma_f32_16x16x32_bf16 v[26:29], v[212:215], v[86:89], v[26:29]
	v_mfma_f32_16x16x32_bf16 v[22:25], v[244:247], v[74:77], v[22:25]
	v_mfma_f32_16x16x32_bf16 v[18:21], v[244:247], v[86:89], v[18:21]
	v_mfma_f32_16x16x32_bf16 v[30:33], v[216:219], v[78:81], v[30:33]
	v_mfma_f32_16x16x32_bf16 v[26:29], v[216:219], v[90:93], v[26:29]
	v_mfma_f32_16x16x32_bf16 v[22:25], v[248:251], v[78:81], v[22:25]
	v_mfma_f32_16x16x32_bf16 v[18:21], v[248:251], v[90:93], v[18:21]
	s_waitcnt lgkmcnt(0)
	v_mfma_f32_16x16x32_bf16 v[10:13], v[94:97], v[74:77], v[10:13]
	v_mfma_f32_16x16x32_bf16 v[14:17], v[94:97], v[86:89], v[14:17]
	v_mfma_f32_16x16x32_bf16 v[6:9], v[102:105], v[74:77], v[6:9]
	v_mfma_f32_16x16x32_bf16 v[2:5], v[102:105], v[86:89], v[2:5]
	v_mfma_f32_16x16x32_bf16 v[10:13], v[98:101], v[78:81], v[10:13]
	v_mfma_f32_16x16x32_bf16 v[14:17], v[98:101], v[90:93], v[14:17]
	v_mfma_f32_16x16x32_bf16 v[6:9], v[134:137], v[78:81], v[6:9]
	v_mfma_f32_16x16x32_bf16 v[2:5], v[134:137], v[90:93], v[2:5]
	s_cmpk_lg_i32 s0, 0x43
	s_waitcnt lgkmcnt(0)
	s_barrier
	s_cbranch_scc0 .LBB0_1282
	v_mov_b64_e32 v[122:123], v[118:119]
	s_branch .Lga_odd
.Lga_odd:
	s_add_i32 s0, s0, 1
	s_add_i32 s1, s0, 1
	s_min_u32 s1, s1, 0x43
	ds_read_b128 v[74:77], v170 offset:17408
	ds_read_b128 v[82:85], v170 offset:19456
	ds_read_b128 v[86:89], v171 offset:17408
	ds_read_b128 v[98:101], v171 offset:19456
	s_lshl_b32 s2, s1, 14
	s_lshl_b32 s56, s1, 7
	v_lshl_add_u64 v[58:59], v[184:185], 0, s[2:3]
	v_lshl_add_u64 v[66:67], v[120:121], 0, s[56:57]
	v_lshl_add_u64 v[68:69], v[186:187], 0, s[2:3]
	v_lshl_add_u64 v[70:71], v[188:189], 0, s[56:57]
	global_load_dwordx4 v[58:61], v[58:59], off
	s_nop 0
	global_load_dwordx4 v[62:65], v[66:67], off
	s_nop 0
	global_load_dwordx4 v[66:69], v[68:69], off
	s_nop 0
	global_load_dwordx4 v[70:73], v[70:71], off
	s_waitcnt lgkmcnt(0)
	v_mfma_f32_16x16x32_bf16 v[78:81], v[74:77], v[46:49], v[152:155]
	v_mfma_f32_16x16x32_bf16 v[74:77], v[74:77], v[50:53], v[156:159]
	v_mfma_f32_16x16x32_bf16 v[94:97], v[86:89], v[42:45], v[78:81]
	v_mfma_f32_16x16x32_bf16 v[78:81], v[86:89], v[54:57], v[74:77]
	v_mfma_f32_16x16x32_bf16 v[74:77], v[82:85], v[46:49], v[152:155]
	v_mfma_f32_16x16x32_bf16 v[90:93], v[98:101], v[42:45], v[74:77]
	v_mfma_f32_16x16x32_bf16 v[74:77], v[82:85], v[50:53], v[156:159]
	ds_read_b128 v[82:85], v170 offset:21504
	ds_read_b128 v[134:137], v170 offset:23552
	v_mfma_f32_16x16x32_bf16 v[74:77], v[98:101], v[54:57], v[74:77]
	ds_read_b128 v[98:101], v171 offset:21504
	ds_read_b128 v[138:141], v171 offset:23552
	s_waitcnt lgkmcnt(0)
	ds_read2_b64 v[212:215], v174 offset1:4
	ds_read2_b64 v[216:219], v174 offset0:8 offset1:12
	ds_read2_b64 v[244:247], v175 offset0:32 offset1:36
	ds_read2_b64 v[248:251], v175 offset0:40 offset1:44
	v_mfma_f32_16x16x32_bf16 v[86:89], v[82:85], v[46:49], v[152:155]
	v_mfma_f32_16x16x32_bf16 v[82:85], v[82:85], v[50:53], v[156:159]
	v_mfma_f32_16x16x32_bf16 v[102:105], v[98:101], v[42:45], v[86:89]
	v_mfma_f32_16x16x32_bf16 v[86:89], v[98:101], v[54:57], v[82:85]
	v_mfma_f32_16x16x32_bf16 v[82:85], v[134:137], v[46:49], v[152:155]
	v_mfma_f32_16x16x32_bf16 v[98:101], v[138:141], v[42:45], v[82:85]
	v_mfma_f32_16x16x32_bf16 v[82:85], v[134:137], v[50:53], v[156:159]
	v_mfma_f32_16x16x32_bf16 v[82:85], v[138:141], v[54:57], v[82:85]
	v_max3_f32 v118, v94, v95, v96
	v_max3_f32 v119, v97, v90, v91
	v_max3_f32 v118, v118, v92, v93
	v_max3_f32 v118, v118, v119, v102
	v_max3_f32 v119, v103, v104, v105
	v_max3_f32 v118, v118, v119, v98
	v_max3_f32 v119, v99, v100, v101
	v_max_f32_e32 v118, v118, v119
	v_mov_b32_e32 v119, v118
	s_nop 1
	v_permlane16_swap_b32_e32 v119, v118
	v_max_f32_e32 v118, v118, v119
	v_mov_b32_e32 v119, v118
	s_nop 1
	v_permlane32_swap_b32_e32 v119, v118
	v_max_f32_e32 v118, v118, v119
	v_cmp_lt_f32_e32 vcc, 0x41000000, v118
	s_cbranch_vccz .Lga_o_1277
	v_max_f32_e32 v119, 0, v118
	v_add_f32_e32 v124, v122, v119
	v_exp_f32_e64 v118, -v119
	v_mov_b32_e32 v125, v123
	v_mov_b32_e32 v122, v124
	v_xor_b32_e32 v152, 0x80000000, v124
	v_mov_b32_e32 v153, v152
	v_mov_b32_e32 v154, v152
	v_mov_b32_e32 v155, v152
	v_sub_f32_e32 v94, v94, v119
	v_sub_f32_e32 v95, v95, v119
	v_sub_f32_e32 v96, v96, v119
	v_sub_f32_e32 v97, v97, v119
	v_sub_f32_e32 v90, v90, v119
	v_sub_f32_e32 v91, v91, v119
	v_sub_f32_e32 v92, v92, v119
	v_sub_f32_e32 v93, v93, v119
	v_sub_f32_e32 v102, v102, v119
	v_sub_f32_e32 v103, v103, v119
	v_sub_f32_e32 v104, v104, v119
	v_sub_f32_e32 v105, v105, v119
	v_sub_f32_e32 v98, v98, v119
	v_sub_f32_e32 v99, v99, v119
	v_sub_f32_e32 v100, v100, v119
	v_sub_f32_e32 v101, v101, v119
	v_pk_mul_f32 v[38:39], v[38:39], v[118:119] op_sel_hi:[1,0]
	v_pk_mul_f32 v[40:41], v[40:41], v[118:119] op_sel_hi:[1,0]
	v_pk_mul_f32 v[32:33], v[32:33], v[118:119] op_sel_hi:[1,0]
	v_pk_mul_f32 v[30:31], v[30:31], v[118:119] op_sel_hi:[1,0]
	v_pk_mul_f32 v[24:25], v[24:25], v[118:119] op_sel_hi:[1,0]
	v_pk_mul_f32 v[22:23], v[22:23], v[118:119] op_sel_hi:[1,0]
	v_pk_mul_f32 v[12:13], v[12:13], v[118:119] op_sel_hi:[1,0]
	v_pk_mul_f32 v[10:11], v[10:11], v[118:119] op_sel_hi:[1,0]
	v_pk_mul_f32 v[8:9], v[8:9], v[118:119] op_sel_hi:[1,0]
	v_pk_mul_f32 v[6:7], v[6:7], v[118:119] op_sel_hi:[1,0]
	s_branch .Lga_o_1278

.Lga_o_1280:
	v_exp_f32_e32 v134, v74
	v_exp_f32_e32 v135, v75
	v_exp_f32_e32 v136, v76
	v_exp_f32_e32 v137, v77
	v_exp_f32_e32 v138, v86
	v_exp_f32_e32 v139, v87
	v_exp_f32_e32 v140, v88
	v_exp_f32_e32 v141, v89
	v_exp_f32_e32 v122, v78
	v_exp_f32_e32 v142, v82
	v_exp_f32_e32 v123, v79
	v_exp_f32_e32 v143, v83
	s_mov_b32 s38, s36
	s_mov_b32 s39, s36
	v_mov_b64_e32 v[118:119], v[124:125]
	v_exp_f32_e32 v124, v80
	v_exp_f32_e32 v144, v84
	v_exp_f32_e32 v125, v85
	s_mov_b32 s37, s36
	v_mov_b64_e32 v[84:85], s[38:39]
	v_exp_f32_e32 v94, v94
	v_exp_f32_e32 v95, v95
	v_exp_f32_e32 v96, v96
	v_exp_f32_e32 v97, v97
	v_exp_f32_e32 v90, v90
	v_exp_f32_e32 v91, v91
	v_exp_f32_e32 v92, v92
	v_exp_f32_e32 v93, v93
	v_exp_f32_e32 v133, v81
	v_mov_b64_e32 v[82:83], s[36:37]
	v_exp_f32_e32 v102, v102
	v_exp_f32_e32 v103, v103
	v_exp_f32_e32 v104, v104
	v_exp_f32_e32 v105, v105
	v_exp_f32_e32 v98, v98
	v_exp_f32_e32 v99, v99
	v_exp_f32_e32 v100, v100
	v_exp_f32_e32 v101, v101
	v_cvt_pk_bf16_f32 v74, v94, v95
	v_cvt_pk_bf16_f32 v75, v96, v97
	v_cvt_pk_bf16_f32 v76, v90, v91
	v_cvt_pk_bf16_f32 v77, v92, v93
	v_cvt_pk_bf16_f32 v86, v122, v123
	v_cvt_pk_bf16_f32 v87, v124, v133
	v_cvt_pk_bf16_f32 v88, v134, v135
	v_cvt_pk_bf16_f32 v89, v136, v137
	v_mfma_f32_16x16x32_bf16 v[38:41], v[82:85], v[74:77], v[38:41]
	v_cvt_pk_bf16_f32 v78, v102, v103
	v_cvt_pk_bf16_f32 v79, v104, v105
	v_cvt_pk_bf16_f32 v80, v98, v99
	v_mfma_f32_16x16x32_bf16 v[34:37], v[82:85], v[86:89], v[34:37]
	v_cvt_pk_bf16_f32 v81, v100, v101
	v_cvt_pk_bf16_f32 v90, v138, v139
	v_cvt_pk_bf16_f32 v91, v140, v141
	v_cvt_pk_bf16_f32 v92, v142, v143
	v_cvt_pk_bf16_f32 v93, v144, v125
	v_mfma_f32_16x16x32_bf16 v[38:41], v[82:85], v[78:81], v[38:41]
	s_nop 0
	v_mfma_f32_16x16x32_bf16 v[34:37], v[82:85], v[90:93], v[34:37]
	s_waitcnt vmcnt(4)
	ds_write_b128 v180, v[228:231]
	ds_write_b128 v182, v[232:235] offset:8192
	ds_write_b128 v181, v[236:239]
	ds_write_b128 v182, v[240:243] offset:12800
	ds_read2_b64 v[94:97], v178 offset0:64 offset1:68
	ds_read2_b64 v[98:101], v178 offset0:72 offset1:76
	ds_read2_b64 v[102:105], v179 offset0:96 offset1:100
	ds_read2_b64 v[134:137], v179 offset0:104 offset1:108
	s_waitcnt lgkmcnt(4)
	v_mfma_f32_16x16x32_bf16 v[30:33], v[212:215], v[74:77], v[30:33]
	v_mfma_f32_16x16x32_bf16 v[26:29], v[212:215], v[86:89], v[26:29]
	v_mfma_f32_16x16x32_bf16 v[22:25], v[244:247], v[74:77], v[22:25]
	v_mfma_f32_16x16x32_bf16 v[18:21], v[244:247], v[86:89], v[18:21]
	v_mfma_f32_16x16x32_bf16 v[30:33], v[216:219], v[78:81], v[30:33]
	v_mfma_f32_16x16x32_bf16 v[26:29], v[216:219], v[90:93], v[26:29]
	v_mfma_f32_16x16x32_bf16 v[22:25], v[248:251], v[78:81], v[22:25]
	v_mfma_f32_16x16x32_bf16 v[18:21], v[248:251], v[90:93], v[18:21]
	s_waitcnt lgkmcnt(0)
	v_mfma_f32_16x16x32_bf16 v[10:13], v[94:97], v[74:77], v[10:13]
	v_mfma_f32_16x16x32_bf16 v[14:17], v[94:97], v[86:89], v[14:17]
	v_mfma_f32_16x16x32_bf16 v[6:9], v[102:105], v[74:77], v[6:9]
	v_mfma_f32_16x16x32_bf16 v[2:5], v[102:105], v[86:89], v[2:5]
	v_mfma_f32_16x16x32_bf16 v[10:13], v[98:101], v[78:81], v[10:13]
	v_mfma_f32_16x16x32_bf16 v[14:17], v[98:101], v[90:93], v[14:17]
	v_mfma_f32_16x16x32_bf16 v[6:9], v[134:137], v[78:81], v[6:9]
	v_mfma_f32_16x16x32_bf16 v[2:5], v[134:137], v[90:93], v[2:5]
	s_cmpk_lg_i32 s0, 0x43
	s_waitcnt lgkmcnt(0)
	s_barrier
	s_cbranch_scc0 .LBB0_1282
	v_mov_b64_e32 v[122:123], v[118:119]
	s_branch .LBB0_1275
